# S5 tables for layer j now built by the S5 workgroups at the start of layer j's scan phase (layer-1 tables no longer built in the prep phase by all workgroups)
# speedup vs baseline: 1.0095x; 1.0095x over previous
; __device__ __forceinline__ int BIDX() { int t = blockIdx.x; asm volatile("" : "+s"(t)); return t; }
; __device__ __forceinline__ char* WS(const Params& p) { return p.ws + opaque0(); }
; #define BAR __builtin_amdgcn_s_barrier()
; #define BAR __builtin_amdgcn_s_barrier()
; __device__ __forceinline__ void gemm_stream(int swave, const GemmJob& J, char* shm, int vb, int G) {
;     ...
;   const int wid = tidx >> 6, lane = tidx & 63, wr = wid >> 2, wc = wid & 3, fr = lane & 15, fq = lane >> 4;
;   unsigned offA0, offA1, offB0;
;   { int _r, _c; stage_rc(tidx * 16, _r, _c); offA0 = _r * lda + _c; offA1 = _r * lda1 + _c; const int _rb = (_r & ~31) + perm32(_r & 31); offB0 = _rb * ldb + _c; }
;   const size_t hB = (size_t)128 * ldb;
;   int cg, cbrow, cbcol; const bf16_t* cA; const bf16_t* cA1; const bf16_t* cB;
;   auto decode = [&](int id, int& g, int& brow, int& bcol, const bf16_t*& pA, const bf16_t*& pA1, const bf16_t*& pB) {
;     int pm, pn; g = 0;
;     if (J.nb == 1) tile_map(id, J.nM, J.nN, pm, pn);
;     else { g = id / per; const int rem = id - g * per; pm = rem / J.nN; pn = rem - pm * J.nN; }
;     brow = pm * 256; bcol = pn * 256;
;     pA = J.A + (size_t)g * J.strideA + (size_t)brow * lda; pA1 = J.A1 + (size_t)g * J.strideA + (size_t)brow * lda1; pB = J.Bt + (size_t)g * J.strideB + (size_t)bcol * ldb;
;   };
;   int id = vb;
;   decode(id, cg, cbrow, cbcol, cA, cA1, cB);
;   f32x4 acc[2][2][4][2] = {};
;   bf16x8 At[4][2], B0[2][2], B1[2][2];
;   STG(SB(0, 0), cB, ldb, offB0); STGA(SA(0, 0), cA, cA1, 0, 0); STG(SB(0, 1), cB + hB, ldb, offB0); STGA(SA(0, 1), cA, cA1, 0, 1);
;   if (wr == 1) BAR;
; __device__ void scan_odd_phase(int swave, const Params& p, int j, char* shm, unsigned* bar) {
;   const int bidx = BIDX();
;   if (bidx < 128) { scan_unit<2>(swave, p, j, bidx >> 3, (bidx >> 1) & 3, bidx & 1, shm); return; }
;   const int vb = bidx - 128, nv = gridDim.x - 128;
;   char* ws = WS(p);
;   {
;     GemmJob J0;
;     set_job(J0, (const bf16_t*)(ws + OFF_A16), DM, (bf16_t*)(ws + OFF_WB) + WB_IN + (size_t)O_SU * DM, DM, TOK, 256, DM, 0, ws + OFF_PU + (size_t)O_SU * 2, nullptr, nullptr, ODD_IN);
;     gemm_run(swave, J0, shm, vb, nv);
.LBB0_74:
	s_andn2_b64 vcc, exec, s[0:1]
	s_cbranch_vccnz .LBB0_700
	v_readlane_b32 s2, v247, 53
	v_readlane_b32 s3, v247, 54
	s_mov_b64 s[0:1], -1
	s_and_b64 vcc, exec, s[2:3]
	s_cbranch_vccz .LBB0_630
	s_mov_b32 s0, s85
	s_cmpk_gt_i32 s0, 0x7f
	v_writelane_b32 v246, s0, 4
	s_cbranch_scc0 .LBB0_469
	s_add_i32 s54, s0, 0xffffff80
	s_lshl_b32 s0, s54, 9
	v_readlane_b32 s1, v247, 47
	v_writelane_b32 v246, s0, 9
	s_add_i32 s1, s1, -1
	s_ashr_i32 s0, s1, 31
	v_writelane_b32 v247, s1, 47
	v_writelane_b32 v247, s0, 48
	s_branch .Ltab_block
.Ltab_return:
	v_readlane_b32 s1, v247, 47
	s_mov_b32 s0, 0
	s_add_i32 s1, s1, 1
	v_writelane_b32 v247, s0, 48
	v_writelane_b32 v247, s1, 47
	s_mov_b32 s0, s85
	v_readlane_b32 s4, v248, 8
	s_add_i32 s54, s0, 0xffffff80
	s_mov_b64 s[0:1], 0
	v_readlane_b32 s6, v248, 10
	v_readlane_b32 s7, v248, 11
	s_add_u32 s74, s6, s0
	s_addc_u32 s75, s7, s1
	v_mov_b32_e32 v135, v147
	s_cmpk_gt_u32 s54, 0x7f
	v_readlane_b32 s5, v248, 9
	s_cbranch_scc1 .LBB0_93
	v_ashrrev_i32_e32 v1, 31, v135
	v_lshrrev_b32_e32 v1, 26, v1
	v_add_u32_e32 v1, v135, v1
	s_waitcnt vmcnt(0)
	v_ashrrev_i32_e32 v6, 6, v1
	v_bfe_i32 v1, v135, 27, 1
	v_lshlrev_b32_e32 v0, 4, v135
	v_lshrrev_b32_e32 v1, 22, v1
	v_add_u32_e32 v1, v0, v1
	v_and_b32_e32 v1, 0xfffffc00, v1
	v_sub_u32_e32 v0, v0, v1
	v_lshrrev_b32_e32 v1, 4, v0
	v_bitop3_b32 v1, v1, v0, 32 bitop3:0x6c
	v_ashrrev_i32_e32 v0, 31, v0
	v_lshrrev_b32_e32 v0, 26, v0
	v_add_u32_e32 v0, v1, v0
	v_ashrrev_i32_e32 v8, 6, v0
	v_lshlrev_b32_e32 v0, 5, v6
	v_and_b32_e32 v9, 32, v0
	v_mul_i32_i24_e32 v0, 64, v8
	v_lshlrev_b32_e32 v2, 3, v6
	v_sub_u32_e32 v0, v1, v0
	v_and_b32_e32 v2, -16, v2
	v_ashrrev_i16_sdwa v10, v149, sext(v0) dst_sel:DWORD dst_unused:UNUSED_PAD src0_sel:DWORD src1_sel:BYTE_0
	v_add_u32_e32 v2, v8, v2
	v_add_u32_sdwa v1, v9, sext(v10) dst_sel:DWORD dst_unused:UNUSED_PAD src0_sel:DWORD src1_sel:WORD_0
	v_and_b32_e32 v11, 3, v8
	s_mov_b32 s2, 0x3fffe0
	s_add_u32 s0, s74, 0x1a500000
	v_lshl_add_u32 v0, v2, 10, v1
	v_lshlrev_b32_e32 v4, 1, v2
	v_lshrrev_b32_e32 v5, 2, v2
	v_and_or_b32 v2, v2, s2, v11
	v_readlane_b32 s2, v246, 4
	s_addc_u32 s1, s75, 0
	s_lshl_b32 s2, s2, 4
	s_lshr_b32 s3, s54, 3
	s_or_b32 s2, s3, s2
	s_and_b32 s6, s2, 0x7f
	v_and_b32_e32 v4, 24, v4
	v_and_b32_e32 v5, 4, v5
	s_lshl_b32 s2, s6, 19
	v_or3_b32 v2, v2, v5, v4
	s_add_u32 s4, s74, s2
	v_lshl_add_u32 v2, v2, 10, v1
	s_addc_u32 s5, s75, 0
	s_add_i32 s14, s89, 0
	v_lshlrev_b64 v[4:5], 1, v[2:3]
	s_add_i32 s15, s14, 0x10000
	v_lshl_add_u64 v[12:13], s[0:1], 0, v[4:5]
	s_mov_b32 m0, s15
	s_mov_b64 s[2:3], 0x1a520000
	global_load_lds_dwordx4 v[12:13], off
	v_lshl_add_u64 v[12:13], s[74:75], 0, v[4:5]
	s_add_i32 s16, s14, 0x12000
	v_lshl_add_u64 v[4:5], v[12:13], 0, s[2:3]
	s_mov_b32 m0, s16
	v_mov_b32_e32 v1, v3
	global_load_lds_dwordx4 v[4:5], off
	v_lshl_add_u64 v[4:5], v[0:1], 1, s[4:5]
	s_mov_b32 m0, s14
	s_mov_b64 s[2:3], 0x20000
	s_add_i32 s17, s14, 0x2000
	global_load_lds_dwordx4 v[4:5], off
	v_lshl_add_u64 v[14:15], v[4:5], 0, s[2:3]
	s_mov_b32 m0, s17
	s_mov_b64 s[2:3], 0x1a540000
	s_add_i32 s18, s14, 0x14000
	global_load_lds_dwordx4 v[14:15], off
	v_lshl_add_u64 v[14:15], v[12:13], 0, s[2:3]
	s_mov_b32 m0, s18
	s_mov_b64 s[2:3], 0x1a560000
	s_add_i32 s19, s14, 0x16000
	global_load_lds_dwordx4 v[14:15], off
	v_lshl_add_u64 v[12:13], v[12:13], 0, s[2:3]
	s_mov_b32 m0, s19
	s_mov_b64 s[2:3], 0x40000
	s_add_i32 s24, s14, 0x4000
	global_load_lds_dwordx4 v[12:13], off
	v_lshl_add_u64 v[12:13], v[4:5], 0, s[2:3]
	s_mov_b32 m0, s24
	s_mov_b64 s[2:3], 0x60000
	s_add_i32 s25, s14, 0x6000
	global_load_lds_dwordx4 v[12:13], off
	v_lshl_add_u64 v[12:13], v[4:5], 0, s[2:3]
	s_mov_b32 m0, s25
	v_ashrrev_i32_e32 v7, 8, v135
	global_load_lds_dwordx4 v[12:13], off
	v_cmp_eq_u32_e32 vcc, 1, v7
	s_and_saveexec_b64 s[2:3], vcc
	s_cbranch_execz .LBB0_80
	s_barrier

; __device__ __forceinline__ const float* INP(const Params& p, int k) { return p.in[k] + opaque0(); }
; __device__ __forceinline__ char* WS(const Params& p) { return p.ws + opaque0(); }
; __device__ void s5_tables(int swave, const Params& p, int j, int bidx, int nblk) {
;   const int tidx = TIDX(swave);
;   const float* lam_re = INP(p, 14) + (size_t)j * 2 * 16 * 64;
;   const float* lam_im = INP(p, 15) + (size_t)j * 2 * 16 * 64;
;   const float* log_dt = INP(p, 16) + (size_t)j * 2 * 16;
;   const float* b_re = INP(p, 17) + (size_t)j * 16 * 64 * 16;
;   const float* b_im = INP(p, 18) + (size_t)j * 16 * 64 * 16;
;   const float* c_re = INP(p, 19) + (size_t)j * 16 * 16 * 64;
;   const float* c_im = INP(p, 20) + (size_t)j * 16 * 16 * 64;
;   bf16_t* TRt = (bf16_t*)(WS(p) + OFF_S5M);
;   bf16_t* Pm = (bf16_t*)(WS(p) + OFF_S5M + S5M_PM);
;   const int gtid = bidx * 512 + tidx, gsz = nblk * 512;
;   for (int it = gtid; it < 16 * 2 * 64 * 64; it += gsz) {
;     const int n = it & 63, t = (it >> 6) & 63, dir = (it >> 12) & 1, g = it >> 13;
; __device__ void scan_odd_phase(int swave, const Params& p, int j, char* shm, unsigned* bar) {
;     ...
;   if (j + 1 < 2) { __syncthreads(); s5_tables(swave, p, j + 1, vb, nv); s5_ktab(swave, p, j + 1, shm, vb, nv); }
.LBB0_470:
	v_readlane_b32 s0, v247, 47
	s_cmp_lt_i32 s0, 1
	s_cselect_b64 s[8:9], -1, 0
	s_and_b64 vcc, exec, s[8:9]
	v_readlane_b32 s1, v247, 48
	s_branch .LBB0_494
.Ltab_block:
	v_readlane_b32 s0, v247, 47
	v_readlane_b32 s1, v247, 48
	s_add_i32 s0, s0, 1
	v_mov_b32_e32 v0, v147
	v_readlane_b32 s12, v246, 9
	s_waitcnt vmcnt(0)
	s_barrier
	s_ashr_i32 s1, s0, 31
	v_add_u32_e32 v24, s12, v0
	s_mov_b32 s12, 0x20000
	s_mov_b64 s[14:15], 0
	s_lshl_b64 s[10:11], s[0:1], 11
	s_mov_b64 s[16:17], 0
	s_mov_b64 s[18:19], 0
	s_lshl_b64 s[6:7], s[0:1], 7
	s_mov_b64 s[42:43], 0
	s_lshl_b64 s[4:5], s[0:1], 14
	s_mov_b64 s[2:3], 0
	s_mov_b64 s[46:47], 0
	s_mov_b64 s[44:45], 0
	s_mov_b64 s[24:25], 0
	s_mov_b64 s[34:35], 0
	v_cmp_gt_i32_e32 vcc, s12, v24
	s_and_saveexec_b64 s[12:13], vcc
	s_cbranch_execz .LBB0_478
	v_readlane_b32 s68, v248, 28
	s_lshl_b64 s[14:15], s[14:15], 2
	v_readlane_b32 s80, v248, 40
	v_readlane_b32 s81, v248, 41
	s_add_u32 s14, s80, s14
	s_addc_u32 s15, s81, s15
	s_lshl_b64 s[20:21], s[10:11], 2
	s_add_u32 s14, s14, s20
	v_readlane_b32 s82, v248, 42
	s_addc_u32 s15, s15, s21
	s_lshl_b64 s[16:17], s[16:17], 2
	v_readlane_b32 s83, v248, 43
	s_add_u32 s16, s82, s16
	s_addc_u32 s17, s83, s17
	v_readlane_b32 s69, v248, 29
	v_readlane_b32 s70, v248, 30
	v_readlane_b32 s71, v248, 31
	v_readlane_b32 s72, v248, 32
	v_readlane_b32 s73, v248, 33
	v_readlane_b32 s74, v248, 34
	v_readlane_b32 s75, v248, 35
	v_readlane_b32 s76, v248, 36
	v_readlane_b32 s77, v248, 37
	v_readlane_b32 s78, v248, 38
	v_readlane_b32 s79, v248, 39
	s_add_u32 s16, s16, s20
	s_addc_u32 s17, s17, s21
	s_lshl_b64 s[18:19], s[18:19], 2
	v_readlane_b32 s68, v248, 44
	v_readlane_b32 s69, v248, 45
	s_add_u32 s18, s68, s18
	s_addc_u32 s19, s69, s19
	v_readlane_b32 s20, v247, 47
	s_add_u32 s18, s18, s6
	v_readlane_b32 s21, v247, 48
	s_addc_u32 s19, s19, s7
	s_lshl_b64 s[20:21], s[20:21], 16
	s_lshl_b64 s[28:29], s[44:45], 2
	s_add_u32 s28, s20, s28
	s_addc_u32 s29, s21, s29
	v_readlane_b32 s33, v247, 14
	s_add_u32 s44, s33, s28
	v_readlane_b32 s28, v247, 15
	s_addc_u32 s45, s28, s29
	s_lshl_b64 s[28:29], s[46:47], 2
	s_add_u32 s20, s20, s28
	s_addc_u32 s21, s21, s29
	v_readlane_b32 s28, v247, 16
	s_add_u32 s46, s28, s20
	v_readlane_b32 s20, v247, 17
	s_addc_u32 s47, s20, s21
	v_readlane_b32 s20, v247, 18
	v_and_b32_e32 v25, 63, v0
	s_add_u32 s20, s20, s24
	v_readlane_b32 s21, v247, 19
	v_lshlrev_b32_e32 v2, 2, v25
	s_addc_u32 s21, s21, s25
	v_or_b32_e32 v26, 0xc0, v25
	v_lshl_add_u64 v[0:1], s[20:21], 0, v[2:3]
	v_or_b32_e32 v2, 0x80, v25
	v_or_b32_e32 v27, 64, v25
	s_mov_b64 s[48:49], 0
	v_mov_b32_e32 v28, v24
	s_movk_i32 s24, 0xf000
	s_mov_b64 s[28:29], 0x2800
	v_readlane_b32 s70, v248, 46
	v_readlane_b32 s71, v248, 47
	v_readlane_b32 s72, v248, 48
	v_readlane_b32 s73, v248, 49
	v_readlane_b32 s74, v248, 50
	v_readlane_b32 s75, v248, 51
	v_readlane_b32 s76, v248, 52
	v_readlane_b32 s77, v248, 53
	v_readlane_b32 s78, v248, 54
	v_readlane_b32 s79, v248, 55
	v_readlane_b32 s80, v248, 56
	v_readlane_b32 s81, v248, 57
	v_readlane_b32 s82, v248, 58
	v_readlane_b32 s83, v248, 59

; __device__ void s5_ktab(int swave, const Params& p, int j, char* shm, int bidx, int nblk) {
;     ...
;       Ktab[((size_t)g * 127 + delta) * 256 + pq * 16 + pp] = accv;
;     }
;   }
;   __syncthreads();
; }
.LBB0_493:
	s_barrier
	s_branch .Ltab_return

; __device__ __forceinline__ int BIDX() { int t = blockIdx.x; asm volatile("" : "+s"(t)); return t; }
; __device__ __forceinline__ const float* INP(const Params& p, int k) { return p.in[k] + opaque0(); }
; __device__ __forceinline__ char* WS(const Params& p) { return p.ws + opaque0(); }
; __device__ void s5_tables(int swave, const Params& p, int j, int bidx, int nblk) {
;   const int tidx = TIDX(swave);
;   const float* lam_re = INP(p, 14) + (size_t)j * 2 * 16 * 64;
;   const float* lam_im = INP(p, 15) + (size_t)j * 2 * 16 * 64;
;   const float* log_dt = INP(p, 16) + (size_t)j * 2 * 16;
;   const float* b_re = INP(p, 17) + (size_t)j * 16 * 64 * 16;
;   const float* b_im = INP(p, 18) + (size_t)j * 16 * 64 * 16;
;   const float* c_re = INP(p, 19) + (size_t)j * 16 * 16 * 64;
;   const float* c_im = INP(p, 20) + (size_t)j * 16 * 16 * 64;
;   bf16_t* TRt = (bf16_t*)(WS(p) + OFF_S5M);
;   bf16_t* Pm = (bf16_t*)(WS(p) + OFF_S5M + S5M_PM);
;   const int gtid = bidx * 512 + tidx, gsz = nblk * 512;
;   for (int it = gtid; it < 16 * 2 * 64 * 64; it += gsz) {
;     const int n = it & 63, t = (it >> 6) & 63, dir = (it >> 12) & 1, g = it >> 13;
; __device__ void prep_phase(int swave, const Params& p, int layer, char* shm) {
;     ...
;   if (layer == 1) { s5_tables(swave, p, j, BIDX(), gridDim.x); s5_ktab(swave, p, j, shm, BIDX(), gridDim.x); }
.LBB0_857:
	s_or_b64 exec, exec, s[0:1]
	s_cbranch_execz .LBB0_882
.LBB0_858:
	s_branch .LBB0_886
.LBB0_859:
	s_mov_b32 s2, s85
	v_mov_b32_e32 v0, v147
	s_mov_b64 s[4:5], 0
	v_lshl_add_u32 v24, s2, 9, v0
	s_mov_b32 s2, 0x20000
	s_mov_b64 s[6:7], 0
	s_mov_b64 s[8:9], 0
	s_mov_b64 s[12:13], 0
	s_mov_b64 s[0:1], 0
	s_mov_b64 s[18:19], 0
	s_mov_b64 s[14:15], 0
	s_mov_b64 s[24:25], 0
	s_mov_b64 s[16:17], 0
	v_cmp_gt_i32_e32 vcc, s2, v24
	s_and_saveexec_b64 s[2:3], vcc
	s_cbranch_execz .LBB0_866
	v_readlane_b32 s68, v248, 28
	s_lshl_b64 s[4:5], s[4:5], 2
	v_readlane_b32 s80, v248, 40
	v_readlane_b32 s81, v248, 41
	s_add_u32 s4, s80, s4
	v_readlane_b32 s82, v248, 42
	s_addc_u32 s5, s81, s5
	s_lshl_b64 s[6:7], s[6:7], 2
	v_readlane_b32 s69, v248, 29
	v_readlane_b32 s70, v248, 30
	v_readlane_b32 s71, v248, 31
	v_readlane_b32 s72, v248, 32
	v_readlane_b32 s73, v248, 33
	v_readlane_b32 s74, v248, 34
	v_readlane_b32 s75, v248, 35
	v_readlane_b32 s76, v248, 36
	v_readlane_b32 s77, v248, 37
	v_readlane_b32 s78, v248, 38
	v_readlane_b32 s79, v248, 39
	v_readlane_b32 s83, v248, 43
	s_add_u32 s6, s82, s6
	s_addc_u32 s7, s83, s7
	s_lshl_b64 s[8:9], s[8:9], 2
	v_readlane_b32 s68, v248, 44
	v_readlane_b32 s69, v248, 45
	s_add_u32 s8, s68, s8
	v_readlane_b32 s76, v248, 52
	s_addc_u32 s9, s69, s9
	s_lshl_b64 s[14:15], s[14:15], 2
	v_readlane_b32 s77, v248, 53
	s_add_u32 s14, s76, s14
	v_readlane_b32 s74, v248, 50
	s_addc_u32 s15, s77, s15
	s_lshl_b64 s[18:19], s[18:19], 2
	v_readlane_b32 s75, v248, 51
	s_add_u32 s18, s74, s18
	s_addc_u32 s19, s75, s19
	v_readlane_b32 s20, v247, 18
	v_and_b32_e32 v25, 63, v0
	s_add_u32 s20, s20, s24
	v_readlane_b32 s21, v247, 19
	v_lshlrev_b32_e32 v2, 2, v25
	s_addc_u32 s21, s21, s25
	v_or_b32_e32 v26, 0xc0, v25
	v_lshl_add_u64 v[0:1], s[20:21], 0, v[2:3]
	v_or_b32_e32 v2, 0x80, v25
	v_or_b32_e32 v27, 64, v25
	s_mov_b64 s[34:35], 0
	s_waitcnt vmcnt(0)
	v_mov_b32_e32 v28, v24
	v_readlane_b32 s70, v248, 46
	v_readlane_b32 s71, v248, 47
	v_readlane_b32 s72, v248, 48
	v_readlane_b32 s73, v248, 49
	v_readlane_b32 s78, v248, 54
	v_readlane_b32 s79, v248, 55
	v_readlane_b32 s80, v248, 56
	v_readlane_b32 s81, v248, 57
	v_readlane_b32 s82, v248, 58
	v_readlane_b32 s83, v248, 59
